# v59 + 12us odd-XCD stagger at P4 start (de-phase HBM-bound epilogue vs K-loops)
# baseline (speedup 1.0000x reference)
.LBB0_782:
	s_or_b64 exec, exec, s[0:1]
	s_andn2_b64 vcc, exec, s[4:5]
	s_waitcnt lgkmcnt(0)
	s_barrier
	s_bfe_u32 s99, s97, 0x10000
	s_cmp_eq_u32 s99, 0
	s_cbranch_scc1 .Lmy_p4_nodelay
	s_mul_i32 s99, s99, 1200
	s_memrealtime s[100:101]
	s_waitcnt lgkmcnt(0)
	s_add_u32 s98, s100, s99

.Lmy_p4_nodelay:
	s_cbranch_vccnz .LBB0_806
	s_ashr_i32 s2, s97, 31
	s_lshr_b32 s0, s2, 29
	s_add_i32 s8, s97, s0
	s_and_b32 s0, s8, -8
	s_sub_i32 s5, s97, s0
	s_cmp_gt_i32 s5, -1
	s_cbranch_scc0 .LBB0_785
	s_lshl_b32 s4, s5, 6
	s_ashr_i32 s0, s8, 3
	s_cbranch_execz .LBB0_786
	s_branch .LBB0_787
